# v21 + grid-barrier release polls without s_sleep 1 (42 poll loops)
# baseline (speedup 1.0000x reference)
; __device__ __forceinline__ unsigned xb_ld(unsigned* p)              { return __hip_atomic_load(p, __ATOMIC_RELAXED, __HIP_MEMORY_SCOPE_AGENT); }
; __device__ __forceinline__ void xcd_barrier_complete(unsigned* bar, unsigned x, unsigned& nloc, unsigned& nx) {
;     const unsigned G = gridDim.x * gridDim.y * gridDim.z;
;     unsigned sum, cnt, mine, sp = 0u;
;     for (;;) {
;         sum = 0u; cnt = 0u; mine = 0u;
; #pragma unroll
;         for (unsigned j = 0; j < 16; ++j) { const unsigned c = xb_ld(&bar[XB_XCNT(j)]); sum += c; cnt += (c > 0u) ? 1u : 0u; mine = (j == x) ? c : mine; }
;         if (sum == G) break;
;         __builtin_amdgcn_s_sleep(1);
;         if ((++sp & 255u) == 0u) { if (xb_ld(&bar[XB_TMO])) break; if (sp > XB_SPIN_CAP) { atomicAdd(&bar[XB_TMO], 1u); break; } }
;     }
;     nloc = mine > 0u ? mine : 1u; nx = cnt > 0u ? cnt : 1u;
; }
.LBB0_130:
	global_load_dword v15, v16, s[76:77] offset:1024 sc1
	s_waitcnt lgkmcnt(0)
	global_load_dword v0, v16, s[76:77] offset:1280 sc1
	global_load_dword v1, v16, s[76:77] offset:1536 sc1
	global_load_dword v2, v16, s[76:77] offset:1792 sc1
	global_load_dword v3, v16, s[76:77] offset:2048 sc1
	global_load_dword v4, v16, s[76:77] offset:2304 sc1
	global_load_dword v5, v16, s[76:77] offset:2560 sc1
	global_load_dword v6, v16, s[76:77] offset:2816 sc1
	global_load_dword v7, v16, s[76:77] offset:3072 sc1
	global_load_dword v8, v16, s[76:77] offset:3328 sc1
	global_load_dword v9, v16, s[76:77] offset:3584 sc1
	global_load_dword v10, v16, s[76:77] offset:3840 sc1
	global_load_dword v11, v16, s[6:7] sc1
	global_load_dword v12, v16, s[8:9] sc1
	global_load_dword v13, v16, s[10:11] sc1
	global_load_dword v14, v16, s[14:15] sc1
	s_mov_b64 s[16:17], -1
	s_mov_b64 s[18:19], -1
	s_waitcnt vmcnt(14)
	v_add_u32_e32 v17, v0, v15
	s_waitcnt vmcnt(13)
	v_add_u32_e32 v17, v17, v1
	s_waitcnt vmcnt(12)
	v_add_u32_e32 v17, v17, v2
	s_waitcnt vmcnt(11)
	v_add_u32_e32 v17, v17, v3
	s_waitcnt vmcnt(10)
	v_add_u32_e32 v17, v17, v4
	s_waitcnt vmcnt(9)
	v_add_u32_e32 v17, v17, v5
	s_waitcnt vmcnt(8)
	v_add_u32_e32 v17, v17, v6
	s_waitcnt vmcnt(7)
	v_add_u32_e32 v17, v17, v7
	s_waitcnt vmcnt(6)
	v_add_u32_e32 v17, v17, v8
	s_waitcnt vmcnt(5)
	v_add_u32_e32 v17, v17, v9
	s_waitcnt vmcnt(4)
	v_add_u32_e32 v17, v17, v10
	s_waitcnt vmcnt(3)
	v_add_u32_e32 v17, v17, v11
	s_waitcnt vmcnt(2)
	v_add_u32_e32 v17, v17, v12
	s_waitcnt vmcnt(1)
	v_add_u32_e32 v17, v17, v13
	s_waitcnt vmcnt(0)
	v_add_u32_e32 v17, v17, v14
	v_cmp_eq_u32_e32 vcc, s13, v17
	s_cbranch_vccnz .LBB0_129
	s_and_b32 s16, s22, 0xff
	s_cmp_eq_u32 s16, 0
	s_mov_b64 s[16:17], -1
	s_mov_b64 s[20:21], -1
	s_cbranch_scc0 .LBB0_134
	global_load_dword v17, v16, s[76:77] offset:512 sc1
	s_waitcnt vmcnt(0)
	v_cmp_eq_u32_e32 vcc, 0, v17
	s_cbranch_vccnz .LBB0_136
	s_mov_b64 s[20:21], 0

; __device__ __forceinline__ unsigned xb_ld(unsigned* p)              { return __hip_atomic_load(p, __ATOMIC_RELAXED, __HIP_MEMORY_SCOPE_AGENT); }
; #define XB_SPIN(cond, bar) do { unsigned _sp = 0; while (cond) { __builtin_amdgcn_s_sleep(1); \
;     if ((++_sp & 255u) == 0u) { if (xb_ld(&(bar)[XB_TMO])) break; if (_sp > XB_SPIN_CAP) { atomicAdd(&(bar)[XB_TMO], 1u); break; } } } } while (0)
; __device__ __forceinline__ void xcd_barrier(const XcdBarrier& b, bool leader) {
;     ...
;             else XB_SPIN(xb_ld(&bar[XB_TOPGEN]) == tg, bar);
.LBB0_148:
	s_and_b32 s22, s13, 0xff
	s_mov_b64 s[20:21], -1
	s_cmp_lg_u32 s22, 0
	s_mov_b64 s[24:25], -1
	s_cbranch_scc1 .LBB0_151
	global_load_dword v2, v0, s[76:77] offset:512 sc1
	s_waitcnt vmcnt(0)
	v_cmp_eq_u32_e32 vcc, 0, v2
	s_cbranch_vccnz .LBB0_153
	s_mov_b64 s[24:25], 0
	s_mov_b64 s[22:23], -1

; __device__ __forceinline__ unsigned xb_ld(unsigned* p)              { return __hip_atomic_load(p, __ATOMIC_RELAXED, __HIP_MEMORY_SCOPE_AGENT); }
; #define XB_SPIN(cond, bar) do { unsigned _sp = 0; while (cond) { __builtin_amdgcn_s_sleep(1); \
;     if ((++_sp & 255u) == 0u) { if (xb_ld(&(bar)[XB_TMO])) break; if (_sp > XB_SPIN_CAP) { atomicAdd(&(bar)[XB_TMO], 1u); break; } } } } while (0)
; __device__ __forceinline__ void xcd_barrier(const XcdBarrier& b, bool leader) {
;     ...
;             XB_SPIN(xb_ld(&bar[XB_XGEN(b.x)]) == gen, bar);
.LBB0_165:
	s_and_b32 s22, s13, 0xff
	s_cmp_lg_u32 s22, 0
	s_mov_b64 s[24:25], -1
	s_cbranch_scc1 .LBB0_168
	global_load_dword v1, v0, s[14:15] sc1
	s_waitcnt vmcnt(0)
	v_cmp_eq_u32_e32 vcc, 0, v1
	s_cbranch_vccnz .LBB0_170
	s_mov_b64 s[24:25], 0
	s_mov_b64 s[22:23], -1

; __device__ __forceinline__ unsigned xb_ld(unsigned* p)              { return __hip_atomic_load(p, __ATOMIC_RELAXED, __HIP_MEMORY_SCOPE_AGENT); }
; __device__ __forceinline__ void xcd_barrier_complete(unsigned* bar, unsigned x, unsigned& nloc, unsigned& nx) {
;     const unsigned G = gridDim.x * gridDim.y * gridDim.z;
;     unsigned sum, cnt, mine, sp = 0u;
;     for (;;) {
;         sum = 0u; cnt = 0u; mine = 0u;
; #pragma unroll
;         for (unsigned j = 0; j < 16; ++j) { const unsigned c = xb_ld(&bar[XB_XCNT(j)]); sum += c; cnt += (c > 0u) ? 1u : 0u; mine = (j == x) ? c : mine; }
;         if (sum == G) break;
;         __builtin_amdgcn_s_sleep(1);
;         if ((++sp & 255u) == 0u) { if (xb_ld(&bar[XB_TMO])) break; if (sp > XB_SPIN_CAP) { atomicAdd(&bar[XB_TMO], 1u); break; } }
;     }
;     nloc = mine > 0u ? mine : 1u; nx = cnt > 0u ? cnt : 1u;
; }
.LBB0_349:
	global_load_dword v15, v16, s[76:77] offset:1024 sc1
	s_waitcnt lgkmcnt(0)
	global_load_dword v0, v16, s[76:77] offset:1280 sc1
	global_load_dword v1, v16, s[76:77] offset:1536 sc1
	global_load_dword v2, v16, s[76:77] offset:1792 sc1
	global_load_dword v3, v16, s[76:77] offset:2048 sc1
	global_load_dword v4, v16, s[76:77] offset:2304 sc1
	global_load_dword v5, v16, s[76:77] offset:2560 sc1
	global_load_dword v6, v16, s[76:77] offset:2816 sc1
	global_load_dword v7, v16, s[76:77] offset:3072 sc1
	global_load_dword v8, v16, s[76:77] offset:3328 sc1
	global_load_dword v9, v16, s[76:77] offset:3584 sc1
	global_load_dword v10, v16, s[76:77] offset:3840 sc1
	global_load_dword v11, v16, s[6:7] sc1
	global_load_dword v12, v16, s[8:9] sc1
	global_load_dword v13, v16, s[10:11] sc1
	global_load_dword v14, v16, s[12:13] sc1
	s_mov_b64 s[14:15], -1
	s_mov_b64 s[16:17], -1
	s_waitcnt vmcnt(14)
	v_add_u32_e32 v17, v0, v15
	s_waitcnt vmcnt(13)
	v_add_u32_e32 v17, v17, v1
	s_waitcnt vmcnt(12)
	v_add_u32_e32 v17, v17, v2
	s_waitcnt vmcnt(11)
	v_add_u32_e32 v17, v17, v3
	s_waitcnt vmcnt(10)
	v_add_u32_e32 v17, v17, v4
	s_waitcnt vmcnt(9)
	v_add_u32_e32 v17, v17, v5
	s_waitcnt vmcnt(8)
	v_add_u32_e32 v17, v17, v6
	s_waitcnt vmcnt(7)
	v_add_u32_e32 v17, v17, v7
	s_waitcnt vmcnt(6)
	v_add_u32_e32 v17, v17, v8
	s_waitcnt vmcnt(5)
	v_add_u32_e32 v17, v17, v9
	s_waitcnt vmcnt(4)
	v_add_u32_e32 v17, v17, v10
	s_waitcnt vmcnt(3)
	v_add_u32_e32 v17, v17, v11
	s_waitcnt vmcnt(2)
	v_add_u32_e32 v17, v17, v12
	s_waitcnt vmcnt(1)
	v_add_u32_e32 v17, v17, v13
	s_waitcnt vmcnt(0)
	v_add_u32_e32 v17, v17, v14
	v_cmp_eq_u32_e32 vcc, s20, v17
	s_cbranch_vccnz .LBB0_348
	s_and_b32 s14, s21, 0xff
	s_cmp_eq_u32 s14, 0
	s_mov_b64 s[14:15], -1
	s_mov_b64 s[18:19], -1
	s_cbranch_scc0 .LBB0_353
	global_load_dword v17, v16, s[76:77] offset:512 sc1
	s_waitcnt vmcnt(0)
	v_cmp_eq_u32_e32 vcc, 0, v17
	s_cbranch_vccnz .LBB0_355
	s_mov_b64 s[18:19], 0

; __device__ __forceinline__ unsigned xb_ld(unsigned* p)              { return __hip_atomic_load(p, __ATOMIC_RELAXED, __HIP_MEMORY_SCOPE_AGENT); }
; #define XB_SPIN(cond, bar) do { unsigned _sp = 0; while (cond) { __builtin_amdgcn_s_sleep(1); \
;     if ((++_sp & 255u) == 0u) { if (xb_ld(&(bar)[XB_TMO])) break; if (_sp > XB_SPIN_CAP) { atomicAdd(&(bar)[XB_TMO], 1u); break; } } } } while (0)
; __device__ __forceinline__ void xcd_barrier(const XcdBarrier& b, bool leader) {
;     ...
;             else XB_SPIN(xb_ld(&bar[XB_TOPGEN]) == tg, bar);
.LBB0_367:
	s_and_b32 s20, s24, 0xff
	s_mov_b64 s[18:19], -1
	s_cmp_lg_u32 s20, 0
	s_mov_b64 s[22:23], -1
	s_cbranch_scc1 .LBB0_370
	global_load_dword v2, v0, s[76:77] offset:512 sc1
	s_waitcnt vmcnt(0)
	v_cmp_eq_u32_e32 vcc, 0, v2
	s_cbranch_vccnz .LBB0_372
	s_mov_b64 s[22:23], 0
	s_mov_b64 s[20:21], -1

; __device__ __forceinline__ unsigned xb_ld(unsigned* p)              { return __hip_atomic_load(p, __ATOMIC_RELAXED, __HIP_MEMORY_SCOPE_AGENT); }
; #define XB_SPIN(cond, bar) do { unsigned _sp = 0; while (cond) { __builtin_amdgcn_s_sleep(1); \
;     if ((++_sp & 255u) == 0u) { if (xb_ld(&(bar)[XB_TMO])) break; if (_sp > XB_SPIN_CAP) { atomicAdd(&(bar)[XB_TMO], 1u); break; } } } } while (0)
; __device__ __forceinline__ void xcd_barrier(const XcdBarrier& b, bool leader) {
;     ...
;             XB_SPIN(xb_ld(&bar[XB_XGEN(b.x)]) == gen, bar);
.LBB0_384:
	s_and_b32 s20, s26, 0xff
	s_cmp_lg_u32 s20, 0
	s_mov_b64 s[22:23], -1
	s_cbranch_scc1 .LBB0_387
	global_load_dword v1, v0, s[12:13] sc1
	s_waitcnt vmcnt(0)
	v_cmp_eq_u32_e32 vcc, 0, v1
	s_cbranch_vccnz .LBB0_389
	s_mov_b64 s[22:23], 0
	s_mov_b64 s[20:21], -1

; __device__ __forceinline__ unsigned xb_ld(unsigned* p)              { return __hip_atomic_load(p, __ATOMIC_RELAXED, __HIP_MEMORY_SCOPE_AGENT); }
; __device__ __forceinline__ void xcd_barrier_complete(unsigned* bar, unsigned x, unsigned& nloc, unsigned& nx) {
;     const unsigned G = gridDim.x * gridDim.y * gridDim.z;
;     unsigned sum, cnt, mine, sp = 0u;
;     for (;;) {
;         sum = 0u; cnt = 0u; mine = 0u;
; #pragma unroll
;         for (unsigned j = 0; j < 16; ++j) { const unsigned c = xb_ld(&bar[XB_XCNT(j)]); sum += c; cnt += (c > 0u) ? 1u : 0u; mine = (j == x) ? c : mine; }
;         if (sum == G) break;
;         __builtin_amdgcn_s_sleep(1);
;         if ((++sp & 255u) == 0u) { if (xb_ld(&bar[XB_TMO])) break; if (sp > XB_SPIN_CAP) { atomicAdd(&bar[XB_TMO], 1u); break; } }
;     }
;     nloc = mine > 0u ? mine : 1u; nx = cnt > 0u ? cnt : 1u;
; }
.LBB0_974:
	global_load_dword v15, v16, s[76:77] offset:1024 sc1
	global_load_dword v0, v16, s[76:77] offset:1280 sc1
	global_load_dword v1, v16, s[76:77] offset:1536 sc1
	global_load_dword v2, v16, s[76:77] offset:1792 sc1
	global_load_dword v3, v16, s[76:77] offset:2048 sc1
	global_load_dword v4, v16, s[76:77] offset:2304 sc1
	global_load_dword v5, v16, s[76:77] offset:2560 sc1
	global_load_dword v6, v16, s[76:77] offset:2816 sc1
	global_load_dword v7, v16, s[76:77] offset:3072 sc1
	global_load_dword v8, v16, s[76:77] offset:3328 sc1
	global_load_dword v9, v16, s[76:77] offset:3584 sc1
	global_load_dword v10, v16, s[76:77] offset:3840 sc1
	global_load_dword v11, v16, s[6:7] sc1
	global_load_dword v12, v16, s[8:9] sc1
	global_load_dword v13, v16, s[10:11] sc1
	global_load_dword v14, v16, s[12:13] sc1
	s_mov_b64 s[14:15], -1
	s_mov_b64 s[16:17], -1
	s_waitcnt vmcnt(14)
	v_add_u32_e32 v17, v0, v15
	s_waitcnt vmcnt(13)
	v_add_u32_e32 v17, v17, v1
	s_waitcnt vmcnt(12)
	v_add_u32_e32 v17, v17, v2
	s_waitcnt vmcnt(11)
	v_add_u32_e32 v17, v17, v3
	s_waitcnt vmcnt(10)
	v_add_u32_e32 v17, v17, v4
	s_waitcnt vmcnt(9)
	v_add_u32_e32 v17, v17, v5
	s_waitcnt vmcnt(8)
	v_add_u32_e32 v17, v17, v6
	s_waitcnt vmcnt(7)
	v_add_u32_e32 v17, v17, v7
	s_waitcnt vmcnt(6)
	v_add_u32_e32 v17, v17, v8
	s_waitcnt vmcnt(5)
	v_add_u32_e32 v17, v17, v9
	s_waitcnt vmcnt(4)
	v_add_u32_e32 v17, v17, v10
	s_waitcnt vmcnt(3)
	v_add_u32_e32 v17, v17, v11
	s_waitcnt vmcnt(2)
	v_add_u32_e32 v17, v17, v12
	s_waitcnt vmcnt(1)
	v_add_u32_e32 v17, v17, v13
	s_waitcnt vmcnt(0)
	v_add_u32_e32 v17, v17, v14
	v_cmp_eq_u32_e32 vcc, s20, v17
	s_cbranch_vccnz .LBB0_973
	s_and_b32 s14, s21, 0xff
	s_cmp_eq_u32 s14, 0
	s_mov_b64 s[14:15], -1
	s_mov_b64 s[18:19], -1
	s_cbranch_scc0 .LBB0_978
	global_load_dword v17, v16, s[76:77] offset:512 sc1
	s_waitcnt vmcnt(0)
	v_cmp_eq_u32_e32 vcc, 0, v17
	s_cbranch_vccnz .LBB0_980
	s_mov_b64 s[18:19], 0

; __device__ __forceinline__ unsigned xb_ld(unsigned* p)              { return __hip_atomic_load(p, __ATOMIC_RELAXED, __HIP_MEMORY_SCOPE_AGENT); }
; __device__ __forceinline__ void xcd_barrier_complete(unsigned* bar, unsigned x, unsigned& nloc, unsigned& nx) {
;     const unsigned G = gridDim.x * gridDim.y * gridDim.z;
;     unsigned sum, cnt, mine, sp = 0u;
;     for (;;) {
;         sum = 0u; cnt = 0u; mine = 0u;
; #pragma unroll
;         for (unsigned j = 0; j < 16; ++j) { const unsigned c = xb_ld(&bar[XB_XCNT(j)]); sum += c; cnt += (c > 0u) ? 1u : 0u; mine = (j == x) ? c : mine; }
;         if (sum == G) break;
;         __builtin_amdgcn_s_sleep(1);
;         if ((++sp & 255u) == 0u) { if (xb_ld(&bar[XB_TMO])) break; if (sp > XB_SPIN_CAP) { atomicAdd(&bar[XB_TMO], 1u); break; } }
;     }
;     nloc = mine > 0u ? mine : 1u; nx = cnt > 0u ? cnt : 1u;
; }
.LBB0_1414:
	global_load_dword v15, v16, s[76:77] offset:1024 sc1
	global_load_dword v0, v16, s[76:77] offset:1280 sc1
	global_load_dword v1, v16, s[76:77] offset:1536 sc1
	global_load_dword v2, v16, s[76:77] offset:1792 sc1
	global_load_dword v3, v16, s[76:77] offset:2048 sc1
	global_load_dword v4, v16, s[76:77] offset:2304 sc1
	global_load_dword v5, v16, s[76:77] offset:2560 sc1
	global_load_dword v6, v16, s[76:77] offset:2816 sc1
	global_load_dword v7, v16, s[76:77] offset:3072 sc1
	global_load_dword v8, v16, s[76:77] offset:3328 sc1
	global_load_dword v9, v16, s[76:77] offset:3584 sc1
	global_load_dword v10, v16, s[76:77] offset:3840 sc1
	global_load_dword v11, v16, s[6:7] sc1
	global_load_dword v12, v16, s[8:9] sc1
	global_load_dword v13, v16, s[10:11] sc1
	global_load_dword v14, v16, s[12:13] sc1
	s_mov_b64 s[14:15], -1
	s_mov_b64 s[16:17], -1
	s_waitcnt vmcnt(14)
	v_add_u32_e32 v17, v0, v15
	s_waitcnt vmcnt(13)
	v_add_u32_e32 v17, v17, v1
	s_waitcnt vmcnt(12)
	v_add_u32_e32 v17, v17, v2
	s_waitcnt vmcnt(11)
	v_add_u32_e32 v17, v17, v3
	s_waitcnt vmcnt(10)
	v_add_u32_e32 v17, v17, v4
	s_waitcnt vmcnt(9)
	v_add_u32_e32 v17, v17, v5
	s_waitcnt vmcnt(8)
	v_add_u32_e32 v17, v17, v6
	s_waitcnt vmcnt(7)
	v_add_u32_e32 v17, v17, v7
	s_waitcnt vmcnt(6)
	v_add_u32_e32 v17, v17, v8
	s_waitcnt vmcnt(5)
	v_add_u32_e32 v17, v17, v9
	s_waitcnt vmcnt(4)
	v_add_u32_e32 v17, v17, v10
	s_waitcnt vmcnt(3)
	v_add_u32_e32 v17, v17, v11
	s_waitcnt vmcnt(2)
	v_add_u32_e32 v17, v17, v12
	s_waitcnt vmcnt(1)
	v_add_u32_e32 v17, v17, v13
	s_waitcnt vmcnt(0)
	v_add_u32_e32 v17, v17, v14
	v_cmp_eq_u32_e32 vcc, s3, v17
	s_cbranch_vccnz .LBB0_1413
	s_and_b32 s14, s20, 0xff
	s_cmp_eq_u32 s14, 0
	s_mov_b64 s[14:15], -1
	s_mov_b64 s[18:19], -1
	s_cbranch_scc0 .LBB0_1418
	global_load_dword v17, v16, s[76:77] offset:512 sc1
	s_waitcnt vmcnt(0)
	v_cmp_eq_u32_e32 vcc, 0, v17
	s_cbranch_vccnz .LBB0_1420
	s_mov_b64 s[18:19], 0

; __device__ __forceinline__ unsigned xb_ld(unsigned* p)              { return __hip_atomic_load(p, __ATOMIC_RELAXED, __HIP_MEMORY_SCOPE_AGENT); }
; #define XB_SPIN(cond, bar) do { unsigned _sp = 0; while (cond) { __builtin_amdgcn_s_sleep(1); \
;     if ((++_sp & 255u) == 0u) { if (xb_ld(&(bar)[XB_TMO])) break; if (_sp > XB_SPIN_CAP) { atomicAdd(&(bar)[XB_TMO], 1u); break; } } } } while (0)
; __device__ __forceinline__ void xcd_barrier(const XcdBarrier& b, bool leader) {
;     ...
;             else XB_SPIN(xb_ld(&bar[XB_TOPGEN]) == tg, bar);
.LBB0_1432:
	s_and_b32 s20, s3, 0xff
	s_mov_b64 s[18:19], -1
	s_cmp_lg_u32 s20, 0
	s_mov_b64 s[22:23], -1
	s_cbranch_scc1 .LBB0_1435
	global_load_dword v2, v0, s[76:77] offset:512 sc1
	s_waitcnt vmcnt(0)
	v_cmp_eq_u32_e32 vcc, 0, v2
	s_cbranch_vccnz .LBB0_1437
	s_mov_b64 s[22:23], 0
	s_mov_b64 s[20:21], -1

; __device__ __forceinline__ unsigned xb_ld(unsigned* p)              { return __hip_atomic_load(p, __ATOMIC_RELAXED, __HIP_MEMORY_SCOPE_AGENT); }
; #define XB_SPIN(cond, bar) do { unsigned _sp = 0; while (cond) { __builtin_amdgcn_s_sleep(1); \
;     if ((++_sp & 255u) == 0u) { if (xb_ld(&(bar)[XB_TMO])) break; if (_sp > XB_SPIN_CAP) { atomicAdd(&(bar)[XB_TMO], 1u); break; } } } } while (0)
; __device__ __forceinline__ void xcd_barrier(const XcdBarrier& b, bool leader) {
;     ...
;             XB_SPIN(xb_ld(&bar[XB_XGEN(b.x)]) == gen, bar);
.LBB0_1453:
	s_and_b32 s20, s3, 0xff
	s_cmp_lg_u32 s20, 0
	s_mov_b64 s[22:23], -1
	s_cbranch_scc1 .LBB0_1456
	global_load_dword v1, v0, s[12:13] sc1
	s_waitcnt vmcnt(0)
	v_cmp_eq_u32_e32 vcc, 0, v1
	s_cbranch_vccnz .LBB0_1458
	s_mov_b64 s[22:23], 0
	s_mov_b64 s[20:21], -1

; __device__ __forceinline__ unsigned xb_ld(unsigned* p)              { return __hip_atomic_load(p, __ATOMIC_RELAXED, __HIP_MEMORY_SCOPE_AGENT); }
; __device__ __forceinline__ void xcd_barrier_complete(unsigned* bar, unsigned x, unsigned& nloc, unsigned& nx) {
;     const unsigned G = gridDim.x * gridDim.y * gridDim.z;
;     unsigned sum, cnt, mine, sp = 0u;
;     for (;;) {
;         sum = 0u; cnt = 0u; mine = 0u;
; #pragma unroll
;         for (unsigned j = 0; j < 16; ++j) { const unsigned c = xb_ld(&bar[XB_XCNT(j)]); sum += c; cnt += (c > 0u) ? 1u : 0u; mine = (j == x) ? c : mine; }
;         if (sum == G) break;
;         __builtin_amdgcn_s_sleep(1);
;         if ((++sp & 255u) == 0u) { if (xb_ld(&bar[XB_TMO])) break; if (sp > XB_SPIN_CAP) { atomicAdd(&bar[XB_TMO], 1u); break; } }
;     }
;     nloc = mine > 0u ? mine : 1u; nx = cnt > 0u ? cnt : 1u;
; }
.LBB0_1947:
	global_load_dword v15, v16, s[76:77] offset:1024 sc1
	s_waitcnt lgkmcnt(0)
	global_load_dword v0, v16, s[76:77] offset:1280 sc1
	global_load_dword v1, v16, s[76:77] offset:1536 sc1
	global_load_dword v2, v16, s[76:77] offset:1792 sc1
	global_load_dword v3, v16, s[76:77] offset:2048 sc1
	global_load_dword v4, v16, s[76:77] offset:2304 sc1
	global_load_dword v5, v16, s[76:77] offset:2560 sc1
	global_load_dword v6, v16, s[76:77] offset:2816 sc1
	global_load_dword v7, v16, s[76:77] offset:3072 sc1
	global_load_dword v8, v16, s[76:77] offset:3328 sc1
	global_load_dword v9, v16, s[76:77] offset:3584 sc1
	global_load_dword v10, v16, s[76:77] offset:3840 sc1
	global_load_dword v11, v16, s[6:7] sc1
	global_load_dword v12, v16, s[8:9] sc1
	global_load_dword v13, v16, s[10:11] sc1
	global_load_dword v14, v16, s[12:13] sc1
	s_mov_b64 s[14:15], -1
	s_mov_b64 s[16:17], -1
	s_waitcnt vmcnt(14)
	v_add_u32_e32 v17, v0, v15
	s_waitcnt vmcnt(13)
	v_add_u32_e32 v17, v17, v1
	s_waitcnt vmcnt(12)
	v_add_u32_e32 v17, v17, v2
	s_waitcnt vmcnt(11)
	v_add_u32_e32 v17, v17, v3
	s_waitcnt vmcnt(10)
	v_add_u32_e32 v17, v17, v4
	s_waitcnt vmcnt(9)
	v_add_u32_e32 v17, v17, v5
	s_waitcnt vmcnt(8)
	v_add_u32_e32 v17, v17, v6
	s_waitcnt vmcnt(7)
	v_add_u32_e32 v17, v17, v7
	s_waitcnt vmcnt(6)
	v_add_u32_e32 v17, v17, v8
	s_waitcnt vmcnt(5)
	v_add_u32_e32 v17, v17, v9
	s_waitcnt vmcnt(4)
	v_add_u32_e32 v17, v17, v10
	s_waitcnt vmcnt(3)
	v_add_u32_e32 v17, v17, v11
	s_waitcnt vmcnt(2)
	v_add_u32_e32 v17, v17, v12
	s_waitcnt vmcnt(1)
	v_add_u32_e32 v17, v17, v13
	s_waitcnt vmcnt(0)
	v_add_u32_e32 v17, v17, v14
	v_cmp_eq_u32_e32 vcc, s3, v17
	s_cbranch_vccnz .LBB0_1946
	s_and_b32 s14, s20, 0xff
	s_cmp_eq_u32 s14, 0
	s_mov_b64 s[14:15], -1
	s_mov_b64 s[18:19], -1
	s_cbranch_scc0 .LBB0_1951
	global_load_dword v17, v16, s[76:77] offset:512 sc1
	s_waitcnt vmcnt(0)
	v_cmp_eq_u32_e32 vcc, 0, v17
	s_cbranch_vccnz .LBB0_1953
	s_mov_b64 s[18:19], 0

; __device__ __forceinline__ unsigned xb_ld(unsigned* p)              { return __hip_atomic_load(p, __ATOMIC_RELAXED, __HIP_MEMORY_SCOPE_AGENT); }
; __device__ __forceinline__ void xcd_barrier_complete(unsigned* bar, unsigned x, unsigned& nloc, unsigned& nx) {
;     const unsigned G = gridDim.x * gridDim.y * gridDim.z;
;     unsigned sum, cnt, mine, sp = 0u;
;     for (;;) {
;         sum = 0u; cnt = 0u; mine = 0u;
; #pragma unroll
;         for (unsigned j = 0; j < 16; ++j) { const unsigned c = xb_ld(&bar[XB_XCNT(j)]); sum += c; cnt += (c > 0u) ? 1u : 0u; mine = (j == x) ? c : mine; }
;         if (sum == G) break;
;         __builtin_amdgcn_s_sleep(1);
;         if ((++sp & 255u) == 0u) { if (xb_ld(&bar[XB_TMO])) break; if (sp > XB_SPIN_CAP) { atomicAdd(&bar[XB_TMO], 1u); break; } }
;     }
;     nloc = mine > 0u ? mine : 1u; nx = cnt > 0u ? cnt : 1u;
; }
.LBB0_2136:
	global_load_dword v15, v16, s[76:77] offset:1024 sc1
	s_waitcnt lgkmcnt(0)
	global_load_dword v0, v16, s[76:77] offset:1280 sc1
	global_load_dword v1, v16, s[76:77] offset:1536 sc1
	global_load_dword v2, v16, s[76:77] offset:1792 sc1
	global_load_dword v3, v16, s[76:77] offset:2048 sc1
	global_load_dword v4, v16, s[76:77] offset:2304 sc1
	global_load_dword v5, v16, s[76:77] offset:2560 sc1
	global_load_dword v6, v16, s[76:77] offset:2816 sc1
	global_load_dword v7, v16, s[76:77] offset:3072 sc1
	global_load_dword v8, v16, s[76:77] offset:3328 sc1
	global_load_dword v9, v16, s[76:77] offset:3584 sc1
	global_load_dword v10, v16, s[76:77] offset:3840 sc1
	global_load_dword v11, v16, s[6:7] sc1
	global_load_dword v12, v16, s[10:11] sc1
	global_load_dword v13, v16, s[12:13] sc1
	global_load_dword v14, v16, s[14:15] sc1
	s_mov_b64 s[16:17], -1
	s_mov_b64 s[18:19], -1
	s_waitcnt vmcnt(14)
	v_add_u32_e32 v17, v0, v15
	s_waitcnt vmcnt(13)
	v_add_u32_e32 v17, v17, v1
	s_waitcnt vmcnt(12)
	v_add_u32_e32 v17, v17, v2
	s_waitcnt vmcnt(11)
	v_add_u32_e32 v17, v17, v3
	s_waitcnt vmcnt(10)
	v_add_u32_e32 v17, v17, v4
	s_waitcnt vmcnt(9)
	v_add_u32_e32 v17, v17, v5
	s_waitcnt vmcnt(8)
	v_add_u32_e32 v17, v17, v6
	s_waitcnt vmcnt(7)
	v_add_u32_e32 v17, v17, v7
	s_waitcnt vmcnt(6)
	v_add_u32_e32 v17, v17, v8
	s_waitcnt vmcnt(5)
	v_add_u32_e32 v17, v17, v9
	s_waitcnt vmcnt(4)
	v_add_u32_e32 v17, v17, v10
	s_waitcnt vmcnt(3)
	v_add_u32_e32 v17, v17, v11
	s_waitcnt vmcnt(2)
	v_add_u32_e32 v17, v17, v12
	s_waitcnt vmcnt(1)
	v_add_u32_e32 v17, v17, v13
	s_waitcnt vmcnt(0)
	v_add_u32_e32 v17, v17, v14
	v_cmp_eq_u32_e32 vcc, s3, v17
	s_cbranch_vccnz .LBB0_2135
	s_and_b32 s16, s22, 0xff
	s_cmp_eq_u32 s16, 0
	s_mov_b64 s[16:17], -1
	s_mov_b64 s[20:21], -1
	s_cbranch_scc0 .LBB0_2140
	global_load_dword v17, v16, s[76:77] offset:512 sc1
	s_waitcnt vmcnt(0)
	v_cmp_eq_u32_e32 vcc, 0, v17
	s_cbranch_vccnz .LBB0_2142
	s_mov_b64 s[20:21], 0

; __device__ __forceinline__ unsigned xb_ld(unsigned* p)              { return __hip_atomic_load(p, __ATOMIC_RELAXED, __HIP_MEMORY_SCOPE_AGENT); }
; #define XB_SPIN(cond, bar) do { unsigned _sp = 0; while (cond) { __builtin_amdgcn_s_sleep(1); \
;     if ((++_sp & 255u) == 0u) { if (xb_ld(&(bar)[XB_TMO])) break; if (_sp > XB_SPIN_CAP) { atomicAdd(&(bar)[XB_TMO], 1u); break; } } } } while (0)
; __device__ __forceinline__ void xcd_barrier(const XcdBarrier& b, bool leader) {
;     ...
;             else XB_SPIN(xb_ld(&bar[XB_TOPGEN]) == tg, bar);
.LBB0_2154:
	s_and_b32 s22, s3, 0xff
	s_mov_b64 s[20:21], -1
	s_cmp_lg_u32 s22, 0
	s_mov_b64 s[24:25], -1
	s_cbranch_scc1 .LBB0_2157
	global_load_dword v2, v0, s[76:77] offset:512 sc1
	s_waitcnt vmcnt(0)
	v_cmp_eq_u32_e32 vcc, 0, v2
	s_cbranch_vccnz .LBB0_2159
	s_mov_b64 s[24:25], 0
	s_mov_b64 s[22:23], -1

; __device__ __forceinline__ unsigned xb_ld(unsigned* p)              { return __hip_atomic_load(p, __ATOMIC_RELAXED, __HIP_MEMORY_SCOPE_AGENT); }
; #define XB_SPIN(cond, bar) do { unsigned _sp = 0; while (cond) { __builtin_amdgcn_s_sleep(1); \
;     if ((++_sp & 255u) == 0u) { if (xb_ld(&(bar)[XB_TMO])) break; if (_sp > XB_SPIN_CAP) { atomicAdd(&(bar)[XB_TMO], 1u); break; } } } } while (0)
; __device__ __forceinline__ void xcd_barrier(const XcdBarrier& b, bool leader) {
;     ...
;             XB_SPIN(xb_ld(&bar[XB_XGEN(b.x)]) == gen, bar);
.LBB0_2171:
	s_and_b32 s22, s3, 0xff
	s_cmp_lg_u32 s22, 0
	s_mov_b64 s[24:25], -1
	s_cbranch_scc1 .LBB0_2174
	global_load_dword v1, v0, s[14:15] sc1
	s_waitcnt vmcnt(0)
	v_cmp_eq_u32_e32 vcc, 0, v1
	s_cbranch_vccnz .LBB0_2176
	s_mov_b64 s[24:25], 0
	s_mov_b64 s[22:23], -1

; __device__ __forceinline__ unsigned xb_ld(unsigned* p)              { return __hip_atomic_load(p, __ATOMIC_RELAXED, __HIP_MEMORY_SCOPE_AGENT); }
; __device__ __forceinline__ void xcd_barrier_complete(unsigned* bar, unsigned x, unsigned& nloc, unsigned& nx) {
;     const unsigned G = gridDim.x * gridDim.y * gridDim.z;
;     unsigned sum, cnt, mine, sp = 0u;
;     for (;;) {
;         sum = 0u; cnt = 0u; mine = 0u;
; #pragma unroll
;         for (unsigned j = 0; j < 16; ++j) { const unsigned c = xb_ld(&bar[XB_XCNT(j)]); sum += c; cnt += (c > 0u) ? 1u : 0u; mine = (j == x) ? c : mine; }
;         if (sum == G) break;
;         __builtin_amdgcn_s_sleep(1);
;         if ((++sp & 255u) == 0u) { if (xb_ld(&bar[XB_TMO])) break; if (sp > XB_SPIN_CAP) { atomicAdd(&bar[XB_TMO], 1u); break; } }
;     }
;     nloc = mine > 0u ? mine : 1u; nx = cnt > 0u ? cnt : 1u;
; }
.LBB0_2372:
	global_load_dword v15, v16, s[76:77] offset:1024 sc1
	s_waitcnt lgkmcnt(0)
	global_load_dword v0, v16, s[76:77] offset:1280 sc1
	global_load_dword v1, v16, s[76:77] offset:1536 sc1
	global_load_dword v2, v16, s[76:77] offset:1792 sc1
	global_load_dword v3, v16, s[76:77] offset:2048 sc1
	global_load_dword v4, v16, s[76:77] offset:2304 sc1
	global_load_dword v5, v16, s[76:77] offset:2560 sc1
	global_load_dword v6, v16, s[76:77] offset:2816 sc1
	global_load_dword v7, v16, s[76:77] offset:3072 sc1
	global_load_dword v8, v16, s[76:77] offset:3328 sc1
	global_load_dword v9, v16, s[76:77] offset:3584 sc1
	global_load_dword v10, v16, s[76:77] offset:3840 sc1
	global_load_dword v11, v16, s[4:5] sc1
	global_load_dword v12, v16, s[6:7] sc1
	global_load_dword v13, v16, s[10:11] sc1
	global_load_dword v14, v16, s[12:13] sc1
	s_mov_b64 s[14:15], -1
	s_mov_b64 s[16:17], -1
	s_waitcnt vmcnt(14)
	v_add_u32_e32 v17, v0, v15
	s_waitcnt vmcnt(13)
	v_add_u32_e32 v17, v17, v1
	s_waitcnt vmcnt(12)
	v_add_u32_e32 v17, v17, v2
	s_waitcnt vmcnt(11)
	v_add_u32_e32 v17, v17, v3
	s_waitcnt vmcnt(10)
	v_add_u32_e32 v17, v17, v4
	s_waitcnt vmcnt(9)
	v_add_u32_e32 v17, v17, v5
	s_waitcnt vmcnt(8)
	v_add_u32_e32 v17, v17, v6
	s_waitcnt vmcnt(7)
	v_add_u32_e32 v17, v17, v7
	s_waitcnt vmcnt(6)
	v_add_u32_e32 v17, v17, v8
	s_waitcnt vmcnt(5)
	v_add_u32_e32 v17, v17, v9
	s_waitcnt vmcnt(4)
	v_add_u32_e32 v17, v17, v10
	s_waitcnt vmcnt(3)
	v_add_u32_e32 v17, v17, v11
	s_waitcnt vmcnt(2)
	v_add_u32_e32 v17, v17, v12
	s_waitcnt vmcnt(1)
	v_add_u32_e32 v17, v17, v13
	s_waitcnt vmcnt(0)
	v_add_u32_e32 v17, v17, v14
	v_cmp_eq_u32_e32 vcc, s20, v17
	s_cbranch_vccnz .LBB0_2371
	s_and_b32 s14, s21, 0xff
	s_cmp_eq_u32 s14, 0
	s_mov_b64 s[14:15], -1
	s_mov_b64 s[18:19], -1
	s_cbranch_scc0 .LBB0_2376
	global_load_dword v17, v16, s[76:77] offset:512 sc1
	s_waitcnt vmcnt(0)
	v_cmp_eq_u32_e32 vcc, 0, v17
	s_cbranch_vccnz .LBB0_2378
	s_mov_b64 s[18:19], 0
